# v23: sb_attn key-block loop K/V prefetch addresses strength-reduced (scalar base stepped per block + 5 per-unit lane offsets, saddr loads) instead of 5 mad_u64 per iteration
# baseline (speedup 1.0000x reference)
; __device__ __forceinline__ void sb_attn(Frame& F) {
;     ...
;         auto weigh = [&](f32x16 s, f32x16 (&o)[2], float& C, bool diag) __attribute__((always_inline)) {
;             if (diag) {
; #pragma unroll
;                 for (int r = 0; r < 16; ++r) { const int key = (r & 3) + 8 * (r >> 2) + 4 * hi; s[r] = (key < r32) ? s[r] : -1e30f; }
;             }
;             float rm[16], bt[16];
; #pragma unroll
;             for (int r = 0; r < 16; ++r) {
;                 const float q1 = fast_rcp(1.0f + __builtin_amdgcn_exp2f(s[r]));
;                 rm[r] = q1;
;                 bt[r] = 1.0f - q1;
;             }
;             float Gs[4], Gp[4];
; #pragma unroll
;             for (int g4 = 0; g4 < 4; ++g4) { Gs[g4] = (rm[4 * g4] * rm[4 * g4 + 1]) * (rm[4 * g4 + 2] * rm[4 * g4 + 3]);
;                 const unsigned own = __builtin_bit_cast(unsigned, Gs[g4]);
;                 const u32x2 sw = __builtin_amdgcn_permlane32_swap(own, own, false, false);
;                 const unsigned r0 = sw.x, r1 = sw.y;
;                 Gp[g4] = __builtin_bit_cast(float, (r0 == own) ? r1 : r0); }
;             float run = C;
;             float a[16];
; #pragma unroll
;     ...
;                 float sfx = run * (hi == 0 ? Gp[g4] : 1.0f);
;                 a[4 * g4 + 3] = bt[4 * g4 + 3] * sfx; sfx *= rm[4 * g4 + 3];
;                 a[4 * g4 + 2] = bt[4 * g4 + 2] * sfx; sfx *= rm[4 * g4 + 2];
;                 a[4 * g4 + 1] = bt[4 * g4 + 1] * sfx; sfx *= rm[4 * g4 + 1];
;                 a[4 * g4 + 0] = bt[4 * g4 + 0] * sfx;
;                 run *= Gs[g4] * Gp[g4];
;             }
;             C = run;
; #pragma unroll
;             for (int s2 = 0; s2 < 2; ++s2) {
;                 u32x4 pw; pw.x = cvt_pk_bf16(a[8 * s2 + 0], a[8 * s2 + 1]); pw.y = cvt_pk_bf16(a[8 * s2 + 2], a[8 * s2 + 3]); pw.z = cvt_pk_bf16(a[8 * s2 + 4], a[8 * s2 + 5]); pw.w = cvt_pk_bf16(a[8 * s2 + 6], a[8 * s2 + 7]);
;                 const bf16x8 pf = __builtin_bit_cast(bf16x8, pw);
; #pragma unroll
;                 for (int dt = 0; dt < 2; ++dt) {
;                     const int dcol = 32 * dt + 16 * ((lane >> 4) & 1) + 4 * (lane & 3);
;                     const int krow = 16 * s2 + 4 * hi + ((lane & 15) >> 2);
;                     const s16x4 t0v = __builtin_bit_cast(s16x4, __builtin_amdgcn_ds_read_tr16_b64_v4i16((LAS s16x4*)(Vb + krow * P64 + dcol * 2)));
.LBB0_309:
	s_nop 10
	v_cndmask_b32_e64 v3, v226, v101, s[38:39]
	v_exp_f32_e32 v3, v3
	v_cndmask_b32_e64 v5, v226, v103, s[42:43]
	v_cndmask_b32_e64 v7, v226, v104, s[44:45]
	v_cndmask_b32_e64 v9, v226, v105, s[46:47]
	v_add_f32_e32 v3, 1.0, v3
	v_rcp_f32_e32 v6, v3
	v_exp_f32_e32 v3, v5
	v_exp_f32_e32 v5, v7
	v_cndmask_b32_e64 v11, v226, v106, s[48:49]
	v_cndmask_b32_e64 v13, v226, v107, s[50:51]
	v_add_f32_e32 v3, 1.0, v3
	v_rcp_f32_e32 v8, v3
	v_exp_f32_e32 v3, v9
	v_add_f32_e32 v5, 1.0, v5
	v_rcp_f32_e32 v10, v5
	v_exp_f32_e32 v5, v11
	v_add_f32_e32 v3, 1.0, v3
	v_cndmask_b32_e64 v14, v226, v108, s[52:53]
	v_rcp_f32_e32 v12, v3
	v_exp_f32_e32 v3, v13
	v_add_f32_e32 v5, 1.0, v5
	v_rcp_f32_e32 v11, v5
	v_exp_f32_e32 v5, v14
	v_cndmask_b32_e64 v15, v226, v109, s[54:55]
	v_add_f32_e32 v3, 1.0, v3
	v_cndmask_b32_e64 v16, v226, v110, s[56:57]
	v_rcp_f32_e32 v13, v3
	v_exp_f32_e32 v3, v15
	v_add_f32_e32 v5, 1.0, v5
	v_rcp_f32_e32 v14, v5
	v_exp_f32_e32 v5, v16
	v_cndmask_b32_e64 v17, v226, v111, s[58:59]
	v_add_f32_e32 v3, 1.0, v3
	v_cndmask_b32_e64 v18, v226, v112, s[60:61]
	v_rcp_f32_e32 v16, v3
	v_exp_f32_e32 v3, v17
	v_add_f32_e32 v5, 1.0, v5
	v_rcp_f32_e32 v15, v5
	v_exp_f32_e32 v5, v18
	v_cndmask_b32_e64 v19, v226, v113, s[62:63]
	v_add_f32_e32 v3, 1.0, v3
	v_cndmask_b32_e64 v20, v226, v114, s[64:65]
	v_rcp_f32_e32 v17, v3
	v_exp_f32_e32 v3, v19
	v_add_f32_e32 v5, 1.0, v5
	v_cndmask_b32_e64 v21, v226, v115, s[66:67]
	v_rcp_f32_e32 v26, v5
	v_exp_f32_e32 v5, v20
	v_exp_f32_e32 v7, v21
	v_add_f32_e32 v3, 1.0, v3
	v_rcp_f32_e32 v28, v3
	v_add_f32_e32 v3, 1.0, v5
	v_rcp_f32_e32 v27, v3
	v_add_f32_e32 v3, 1.0, v7
	v_rcp_f32_e32 v29, v3
	v_pk_mul_f32 v[18:19], v[10:11], v[12:13]
	v_cndmask_b32_e64 v2, v226, v100, s[36:37]
	v_cndmask_b32_e64 v4, v226, v102, s[40:41]
	v_pk_mul_f32 v[18:19], v[18:19], v[18:19] op_sel:[0,1] op_sel_hi:[1,0]
	v_exp_f32_e32 v2, v2
	v_exp_f32_e32 v4, v4
	v_mov_b32_e32 v3, v18
	v_mov_b32_e32 v5, v18
	v_pk_mul_f32 v[20:21], v[14:15], v[16:17]
	v_pk_mul_f32 v[22:23], v[26:27], v[28:29]
	v_permlane32_swap_b32_e32 v3, v5
	v_mov_b32_e32 v24, v22
	v_mov_b32_e32 v25, v20
	v_mov_b32_e32 v20, v23
	v_cmp_eq_u32_e32 vcc, v3, v18
	v_pk_mul_f32 v[20:21], v[24:25], v[20:21]
	v_add_f32_e32 v2, 1.0, v2
	v_cndmask_b32_e32 v7, v3, v5, vcc
	v_mov_b32_e32 v3, v21
	v_mov_b32_e32 v5, v21
	v_add_f32_e32 v4, 1.0, v4
	s_nop 0
	v_permlane32_swap_b32_e32 v3, v5
	v_mov_b32_e32 v9, v20
	v_mov_b32_e32 v19, v20
	v_rcp_f32_e32 v2, v2
	v_rcp_f32_e32 v4, v4
	v_permlane32_swap_b32_e32 v9, v19
	v_cmp_eq_u32_e32 vcc, v3, v21
	v_cndmask_b32_e64 v22, 1.0, v7, s[68:69]
	v_mov_b32_e32 v32, v26
	v_cndmask_b32_e32 v3, v3, v5, vcc
	v_cmp_eq_u32_e32 vcc, v9, v20
	v_cndmask_b32_e64 v24, 1.0, v3, s[68:69]
	v_mov_b32_e32 v33, v28
	v_cndmask_b32_e32 v5, v9, v19, vcc
	v_cndmask_b32_e64 v39, 1.0, v5, s[68:69]
	v_mul_f32_e32 v9, v20, v5
	v_mul_f32_e32 v5, v21, v3
	v_mov_b32_e32 v3, v18
	v_pk_mul_f32 v[20:21], v[4:5], v[8:9]
	v_pk_mul_f32 v[18:19], v[2:3], v[6:7]
	v_mul_f32_e32 v38, v29, v39
	v_pk_mul_f32 v[46:47], v[18:19], v[20:21]
	v_mul_f32_e32 v19, v22, v21
	v_mul_f32_e32 v18, v13, v19
	v_mov_b32_e32 v3, v46
	v_mov_b32_e32 v5, v46
	v_mul_f32_e32 v23, v11, v18
	s_nop 0
	v_permlane32_swap_b32_e32 v3, v5
	v_mov_b32_e32 v21, v12
	v_mul_f32_e32 v22, v12, v23
	v_mov_b32_e32 v12, v11
	v_cmp_eq_u32_e32 vcc, v3, v46
	v_mov_b32_e32 v20, v10
	v_pk_add_f32 v[10:11], v[12:13], 1.0 op_sel_hi:[1,0] neg_lo:[1,0] neg_hi:[1,0]
	v_mul_f32_e32 v13, v24, v9
	v_cndmask_b32_e32 v50, v3, v5, vcc
	v_pk_add_f32 v[20:21], v[20:21], 1.0 op_sel_hi:[1,0] neg_lo:[1,0] neg_hi:[1,0]
	v_mul_f32_e32 v12, v17, v13
	v_cndmask_b32_e64 v3, 1.0, v50, s[68:69]
	v_pk_mul_f32 v[20:21], v[20:21], v[22:23]
	v_mul_f32_e32 v23, v15, v12
	v_pk_mul_f32 v[10:11], v[10:11], v[18:19]
	v_mov_b32_e32 v18, v14
	v_mov_b32_e32 v19, v16
	v_mul_f32_e32 v22, v16, v23
	v_mov_b32_e32 v16, v15
	v_mul_f32_e32 v9, v3, v47
	v_pk_add_f32 v[18:19], v[18:19], 1.0 op_sel_hi:[1,0] neg_lo:[1,0] neg_hi:[1,0]
	v_pk_add_f32 v[14:15], v[16:17], 1.0 op_sel_hi:[1,0] neg_lo:[1,0] neg_hi:[1,0]
	v_mov_b32_e32 v5, v8
	v_mul_f32_e32 v8, v8, v9
	v_mov_b32_e32 v3, v6
	v_pk_mul_f32 v[40:41], v[18:19], v[22:23]
	v_pk_mul_f32 v[42:43], v[14:15], v[12:13]
	v_pk_add_f32 v[12:13], v[4:5], 1.0 op_sel_hi:[1,0] neg_lo:[1,0] neg_hi:[1,0]
	v_pk_add_f32 v[14:15], v[2:3], 1.0 op_sel_hi:[1,0] neg_lo:[1,0] neg_hi:[1,0]
	v_mul_f32_e32 v7, v4, v8
	ds_read_b64_tr_b16 v[2:3], v209 offset:40960
	ds_read_b64_tr_b16 v[4:5], v209 offset:42112
	ds_read_b64_tr_b16 v[24:25], v209 offset:42176
	ds_read_b64_tr_b16 v[22:23], v209 offset:41024
	v_mul_f32_e32 v6, v6, v7
	v_mul_f32_e32 v31, v27, v38
	v_pk_mul_f32 v[12:13], v[12:13], v[8:9]
	v_pk_mul_f32 v[6:7], v[14:15], v[6:7]
	v_mul_f32_e32 v30, v28, v31
	v_cvt_pk_bf16_f32 v18, v6, v7
	v_cvt_pk_bf16_f32 v19, v12, v13
	v_cvt_pk_bf16_f32 v20, v20, v21
	v_cvt_pk_bf16_f32 v21, v10, v11
	v_pk_add_f32 v[32:33], v[32:33], 1.0 op_sel_hi:[1,0] neg_lo:[1,0] neg_hi:[1,0]
	v_mov_b32_e32 v28, v27
	s_waitcnt lgkmcnt(2)
	v_mfma_f32_32x32x16_bf16 v[2:17], v[2:5], v[18:21], 0
	v_mul_f32_e64 v44, v32, v30
	v_mul_f32_e64 v45, v33, v31
	v_add_f32_e64 v48, -v28, 1.0
	v_add_f32_e64 v49, -v29, 1.0
	ds_read_b64_tr_b16 v[34:35], v209 offset:43264
	ds_read_b64_tr_b16 v[36:37], v209 offset:44416
	v_pk_mul_f32 v[48:49], v[48:49], v[38:39]
	v_cvt_pk_bf16_f32 v38, v40, v41
	v_cvt_pk_bf16_f32 v39, v42, v43
	v_cvt_pk_bf16_f32 v40, v44, v45
	s_waitcnt lgkmcnt(2)
	v_mfma_f32_32x32x16_bf16 v[18:33], v[22:25], v[18:21], 0
	ds_read_b64_tr_b16 v[44:45], v209 offset:44480
	ds_read_b64_tr_b16 v[42:43], v209 offset:43328
	v_cvt_pk_bf16_f32 v41, v48, v49
	s_waitcnt lgkmcnt(2)
	s_nop 0
	v_mfma_f32_32x32x16_bf16 v[2:17], v[34:37], v[38:41], v[2:17]
	v_mul_f32_e32 v34, v46, v50
	v_mul_f32_e32 v231, v34, v47
	v_cmp_gt_f32_e32 vcc, s25, v231
	s_cmp_eq_u64 vcc, exec
	s_cselect_b64 s[72:73], -1, 0
	s_and_b64 s[24:25], s[12:13], s[72:73]
	s_or_b64 s[24:25], s[90:91], s[24:25]
	s_waitcnt lgkmcnt(0)
	v_mfma_f32_32x32x16_bf16 v[18:33], v[42:45], v[38:41], v[18:33]
	s_andn2_b64 vcc, exec, s[24:25]
	s_mov_b64 s[24:25], -1
	s_cbranch_vccz .LBB0_321
; #define LAS __attribute__((address_space(3)))
; __device__ __forceinline__ void sb_attn(Frame& F) {
;     ...
;             const bool actU = !doneU, actL = (kb <= qL) && !doneL;
; #pragma unroll
;             for (int n = 0; n < 4; ++n) { const int idx = lane + 64 * n; *(LAS u32x4*)(Vb + (idx >> 3) * P64 + (idx & 7) * 16) = vreg[n]; }
;             if (actU) { const f32x16 sU = scores(1); weigh(sU, oU, CU, kb == qU); doneU = __all(CU < 0x1p-120f); }
;             f32x16 sL;
;             if (actL) sL = scores(0);
;             if (kb > 0) {
;                 const bf16* Kp = PROJ + (tok0 + 32 * (kb - 1) + r32) * NPROJ + C_SK + 64 * h + 8 * hi;
	s_bfe_u32 s25, s7, 0x60001
	s_lshl_b32 s24, s25, 1
	s_lshl_b32 s25, s25, 6
	v_mov_b64_e32 v[130:131], v[98:99]
	v_mov_b64_e32 v[146:147], v[82:83]
	s_mov_b32 s30, 0x3800000
	s_add_i32 s24, s24, -1
	s_sub_i32 s25, s25, 64
	v_mov_b64_e32 v[128:129], v[96:97]
	v_mov_b64_e32 v[126:127], v[94:95]
	v_mov_b64_e32 v[124:125], v[92:93]
	v_mov_b64_e32 v[122:123], v[90:91]
	v_mov_b64_e32 v[120:121], v[88:89]
	v_mov_b64_e32 v[118:119], v[86:87]
	v_mov_b64_e32 v[116:117], v[84:85]
	v_mov_b64_e32 v[144:145], v[80:81]
	v_mov_b64_e32 v[142:143], v[78:79]
	v_mov_b64_e32 v[140:141], v[76:77]
	v_mov_b64_e32 v[138:139], v[74:75]
	v_mov_b64_e32 v[136:137], v[72:73]
	v_mov_b64_e32 v[134:135], v[70:71]
	v_mov_b64_e32 v[132:133], v[68:69]
	v_mov_b32_e32 v34, v2
	v_mov_b32_e32 v35, v3
	v_mov_b32_e32 v36, v4
	v_mov_b32_e32 v37, v5
	v_mov_b32_e32 v38, v6
	v_mov_b32_e32 v39, v7
	v_mov_b32_e32 v40, v8
	v_mov_b32_e32 v41, v9
	v_mov_b32_e32 v42, v10
	v_mov_b32_e32 v43, v11
	v_mov_b32_e32 v44, v12
	v_mov_b32_e32 v45, v13
	v_mov_b32_e32 v46, v14
	v_mov_b32_e32 v47, v15
	v_mov_b32_e32 v48, v16
	v_mov_b32_e32 v49, v17
	v_mov_b32_e32 v50, v18
	v_mov_b32_e32 v51, v19
	v_mov_b32_e32 v52, v20
	v_mov_b32_e32 v53, v21
	v_mov_b32_e32 v54, v22
	v_mov_b32_e32 v55, v23
	v_mov_b32_e32 v56, v24
	v_mov_b32_e32 v57, v25
	v_mov_b32_e32 v58, v26
	v_mov_b32_e32 v59, v27
	v_mov_b32_e32 v60, v28
	v_mov_b32_e32 v61, v29
	v_mov_b32_e32 v62, v30
	v_mov_b32_e32 v63, v31
	v_mov_b32_e32 v64, v32
	v_mov_b32_e32 v65, v33
	s_add_i32 s100, s10, s25
	s_mul_i32 s100, s100, s81
	s_add_u32 s100, s8, s100
	s_addc_u32 s101, s9, 0
	s_add_u32 s100, s100, s16
	s_addc_u32 s101, s101, s17
	s_add_u32 s100, s100, 0x39000
	s_addc_u32 s101, s101, 0
	v_mad_u32_u24 v239, v204, s81, v66
	v_mad_u32_u24 v240, v206, s81, v214
	v_mad_u32_u24 v241, v208, s81, v214
	v_mad_u32_u24 v242, v210, s81, v214
	v_mad_u32_u24 v243, v212, s81, v214
	s_branch .LBB0_312

; __device__ __forceinline__ void sb_attn(Frame& F) {
;     ...
;             if (kb > 0) {
;                 const bf16* Kp = PROJ + (tok0 + 32 * (kb - 1) + r32) * NPROJ + C_SK + 64 * h + 8 * hi;
; #pragma unroll
;                 for (int ds = 0; ds < 4; ++ds) kf[ds] = *(const bf16x8*)(Kp + 16 * ds);
; #pragma unroll
;                 for (int n = 0; n < 4; ++n) { const int idx = lane + 64 * n; vreg[n] = *(const u32x4*)(PROJ + (tok0 + 32 * (kb - 1) + (idx >> 3)) * NPROJ + C_SV + 64 * h + 8 * (idx & 7)); }
;             }
.LBB0_316:
	v_sub_co_u32_e64 v148, s[90:91], s24, 1
	s_nop 0
	v_readfirstlane_b32 s24, v148
	s_and_b64 vcc, exec, s[90:91]
	s_cbranch_vccnz .LBB0_318
	s_add_u32 s100, s100, 0xfffc8000
	s_addc_u32 s101, s101, -1
	v_mov_b32_e32 v215, v67
	global_load_dwordx4 v[168:171], v239, s[100:101] offset:1056
	global_load_dwordx4 v[172:175], v239, s[100:101] offset:1088
	global_load_dwordx4 v[164:167], v239, s[100:101] offset:1024
	global_load_dwordx4 v[176:179], v239, s[100:101] offset:1120
	global_load_dwordx4 v[180:183], v240, s[100:101] offset:2048
	global_load_dwordx4 v[184:187], v241, s[100:101] offset:2048
	global_load_dwordx4 v[188:191], v242, s[100:101] offset:2048
	global_load_dwordx4 v[192:195], v243, s[100:101] offset:2048
